# state-only HGRN pass: next-step z values unpacked straight from their load registers at the loop top, four rotation copies per step removed
# baseline (speedup 1.0000x reference)
; template <bool FULL>
; __device__ __forceinline__ void hgrn_item(LAS unsigned char* lds, const bf16_t* P, bf16_t* AB, int L, int hd, const float* lbv, const float* anorm, const float* S0, const float* Dd, int ns, float* Sout, float* Dout) {
;     ...
;     const float lb = lbv[k], oml = 1.f - lb;
;     const float an = FULL ? anorm[16 * w + c16] : 0.f;
;     f32x4 accS[8];
; #pragma unroll
;     for (int mt = 0; mt < 8; ++mt) accS[mt] = (f32x4){0.f, 0.f, 0.f, 0.f};
;     if (Dd) {
; #pragma unroll 2
;         for (int c = 0; c < ns; ++c) { const float* sc = S0 + (size_t)c * 16384 + tid;
; #pragma unroll
;             for (int mt = 0; mt < 8; ++mt) { const f32x4 d4 = *(const f32x4*)(Dd + c * 128 + 16 * mt + 4 * q4);
; #pragma unroll
;                 for (int j = 0; j < 4; ++j) accS[mt][j] = accS[mt][j] * d4[j] + sc[(mt * 4 + j) * 512]; } }
;     } else {
;         for (int c = 0; c < ns; ++c) { const float* sc = S0 + (size_t)c * 16384 + 16 * w + c16;
; #pragma unroll
;             for (int mt = 0; mt < 8; ++mt)
; #pragma unroll
;                 for (int j = 0; j < 4; ++j) accS[mt][j] = sc[(size_t)(16 * mt + 4 * q4 + j) * 128]; }
;     }
;     const bf16_t* pq = P + 128 * hd + k + (size_t)(4 * tq) * N1;
;     const bf16_t* pz = pq + 512;
;     const int vt = (tid >> 4) & 15, vc = tid & 15;
;     const bf16_t* pv = P + 1024 + 128 * hd + 8 * vc + (size_t)vt * N1;
;     const bf16_t* pg = P + 1536 + 128 * hd + 16 * w + c16 + (size_t)(4 * q4) * N1;
;     bf16_t* po = AB + 128 * hd + 16 * w + c16 + (size_t)(4 * q4) * D;
;     const int nsteps = L >> 4;
;     float btot = 0.f;
;     unsigned short zr[4], qr[4], grn[4]; u32x4 vr = (u32x4){0u, 0u, 0u, 0u};
; #pragma unroll
;     for (int i = 0; i < 4; ++i) { zr[i] = pz[(size_t)i * N1]; qr[i] = pq[(size_t)i * N1]; grn[i] = pg[(size_t)i * N1]; }
;     if (tid < 256) vr = *(const u32x4*)pv;
;     for (int n = 0; n < nsteps; ++n) {
;         unsigned short zc[4], qc[4], gr[4]; const u32x4 vcur = vr;
; #pragma unroll
;         for (int i = 0; i < 4; ++i) { zc[i] = zr[i]; qc[i] = qr[i]; gr[i] = grn[i]; }
;         const size_t roff = (size_t)(16 * n) * N1;
;         {
;             const size_t nro = (size_t)(16 * (n + 1 < nsteps ? n + 1 : n)) * N1;
; #pragma unroll
;             for (int i = 0; i < 4; ++i) { zr[i] = pz[nro + (size_t)i * N1]; qr[i] = pq[nro + (size_t)i * N1]; grn[i] = pg[nro + (size_t)i * N1]; }
.LBB0_224:
	s_or_b64 exec, exec, s[2:3]
	v_mad_i64_i32 v[8:9], s[2:3], v6, s97, 0
	s_movk_i32 s2, 0x80
	v_lshrrev_b32_e32 v3, 2, v40
	v_and_b32_e32 v7, 15, v40
	v_cmp_gt_u32_e64 s[38:39], s2, v40
	s_mov_b32 s2, 0x1ffffff0
	v_lshrrev_b32_e32 v10, 1, v40
	v_and_or_b32 v3, v3, s2, v7
	s_movk_i32 s2, 0x220
	v_lshl_add_u32 v49, v0, 2, 0
	v_and_b32_e32 v56, 24, v10
	v_mul_u32_u24_e32 v10, 40, v0
	v_cmp_lt_i32_e64 s[46:47], 0, v1
	v_cmp_lt_i32_e64 s[44:45], 1, v1
	v_cmp_lt_i32_e64 s[42:43], 2, v1
	v_cmp_lt_i32_e64 s[40:41], 3, v1
	v_mad_u64_u32 v[0:1], s[2:3], v1, s2, v[0:1]
	v_readlane_b32 s2, v248, 1
	v_mul_u32_u24_e32 v5, 40, v5
	v_lshlrev_b32_e32 v4, 1, v4
	v_lshl_add_u32 v51, v0, 1, 0
	v_lshl_add_u64 v[0:1], v[8:9], 0, v[194:195]
	v_readlane_b32 s3, v248, 2
	v_add3_u32 v41, 0, v5, v4
	v_mul_lo_u32 v4, v3, 40
	v_lshl_add_u64 v[42:43], s[2:3], 0, v[0:1]
	v_lshlrev_b32_e32 v194, 4, v7
	v_mov_b32_e32 v3, v195
	v_readlane_b32 s2, v248, 3
	v_lshl_add_u32 v6, v6, 1, 0
	v_add_u32_e32 v57, 0, v56
	v_mul_u32_u24_e32 v5, 40, v7
	v_lshl_add_u64 v[0:1], v[194:195], 0, v[2:3]
	v_readlane_b32 s3, v248, 4
	v_mov_b32_e32 v48, 0
	s_waitcnt vmcnt(0)
	v_mov_b64_e32 v[32:33], v[36:37]
	v_sub_f32_e32 v55, 1.0, v53
	v_lshl_add_u32 v54, v40, 2, 0
	v_lshl_add_u64 v[44:45], s[2:3], 0, v[0:1]
	s_mov_b64 s[2:3], 0
	v_add_u32_e32 v52, v6, v10
	v_add_u32_e32 v50, v57, v4
	v_add_u32_e32 v58, v57, v5
	v_mov_b32_e32 v0, 0
	v_mov_b32_e32 v1, v48
	v_mov_b32_e32 v2, v48
	v_mov_b32_e32 v3, v48
	v_mov_b32_e32 v28, 0
	v_mov_b32_e32 v29, v48
	v_mov_b32_e32 v30, v48
	v_mov_b32_e32 v31, v48
	v_mov_b32_e32 v24, 0
	v_mov_b32_e32 v25, v48
	v_mov_b32_e32 v26, v48
	v_mov_b32_e32 v27, v48
	v_mov_b32_e32 v20, 0
	v_mov_b32_e32 v21, v48
	v_mov_b32_e32 v22, v48
	v_mov_b32_e32 v23, v48
	v_mov_b32_e32 v16, 0
	v_mov_b32_e32 v17, v48
	v_mov_b32_e32 v18, v48
	v_mov_b32_e32 v19, v48
	v_mov_b32_e32 v12, 0
	v_mov_b32_e32 v13, v48
	v_mov_b32_e32 v14, v48
	v_mov_b32_e32 v15, v48
	v_mov_b32_e32 v8, 0
	v_mov_b32_e32 v9, v48
	v_mov_b32_e32 v10, v48
	v_mov_b32_e32 v11, v48
	v_mov_b32_e32 v4, 0
	v_mov_b32_e32 v5, v48
	v_mov_b32_e32 v6, v48
	v_mov_b32_e32 v7, v48
	v_mov_b64_e32 v[34:35], v[38:39]
	v_mov_b32_e32 v66, v72
	v_mov_b32_e32 v64, v70
	v_mov_b32_e32 v63, v68
	v_mov_b32_e32 v61, v47
.LBB0_225:
	v_lshlrev_b32_e32 v72, 16, v66
	v_lshlrev_b32_e32 v70, 16, v64
	v_lshlrev_b32_e32 v68, 16, v63
	v_lshlrev_b32_e32 v47, 16, v61
	v_lshl_add_u64 v[74:75], v[42:43], 0, s[2:3]
	s_mov_b32 s4, 0x10c2c000
	v_add_co_u32_e32 v60, vcc, s4, v74
	s_mov_b32 s4, 0x10c2f000
	s_nop 0
	v_addc_co_u32_e32 v61, vcc, 0, v75, vcc
	global_load_ushort v66, v[60:61], off offset:1024
	v_add_co_u32_e32 v60, vcc, s4, v74
	s_nop 0
	v_addc_co_u32_e32 v61, vcc, 0, v75, vcc
	global_load_ushort v64, v[60:61], off
	v_add_co_u32_e32 v60, vcc, 0x10c31000, v74
	s_nop 1
	v_addc_co_u32_e32 v61, vcc, 0, v75, vcc
	v_add_co_u32_e32 v74, vcc, 0x10c34000, v74
	global_load_ushort v63, v[60:61], off offset:3072
	v_addc_co_u32_e32 v75, vcc, 0, v75, vcc
	global_load_ushort v61, v[74:75], off offset:2048
	s_and_saveexec_b64 s[4:5], s[36:37]
	s_cbranch_execz .LBB0_227
	v_lshl_add_u64 v[32:33], v[44:45], 0, s[2:3]
	global_load_dwordx4 v[32:35], v[32:33], off
.LBB0_227:
	s_or_b64 exec, exec, s[4:5]
	v_med3_f32 v68, v68, s29, v225
	v_mul_f32_e32 v68, 0xbfb8aa3b, v68
	v_exp_f32_e32 v68, v68
	v_med3_f32 v72, v72, s29, v225
	v_mul_f32_e32 v72, 0xbfb8aa3b, v72
	v_med3_f32 v70, v70, s29, v225
	v_exp_f32_e32 v72, v72
	v_mul_f32_e32 v70, 0xbfb8aa3b, v70
	v_exp_f32_e32 v70, v70
	v_add_f32_e32 v69, 1.0, v68
	v_med3_f32 v47, v47, s29, v225
	v_rcp_f32_e32 v69, v69
	v_mul_f32_e32 v47, 0xbfb8aa3b, v47
	v_exp_f32_e32 v47, v47
	v_add_f32_e32 v73, 1.0, v72
	v_rcp_f32_e32 v73, v73
	v_add_f32_e32 v71, 1.0, v70
	v_rcp_f32_e32 v71, v71
	v_mul_f32_e32 v68, v68, v69
	v_mul_f32_e32 v78, v55, v68
	v_add_f32_e32 v68, 1.0, v47
	v_rcp_f32_e32 v68, v68
	v_mul_f32_e32 v72, v72, v73
	v_fma_f32 v73, v55, v73, v53
	v_log_f32_e32 v73, v73
	v_mul_f32_e32 v70, v70, v71
	v_fma_f32 v71, v55, v71, v53
	v_log_f32_e32 v71, v71
	v_fma_f32 v69, v55, v69, v53
	v_log_f32_e32 v69, v69
	v_mul_f32_e32 v47, v47, v68
	v_fma_f32 v68, v55, v68, v53
	v_log_f32_e32 v68, v68
	v_add_f32_e32 v75, v71, v73
	v_mul_f32_e32 v79, v55, v47
	v_add_f32_e32 v47, v69, v75
	v_add_f32_e32 v81, v68, v47
	ds_write_b32 v54, v81 offset:19456
	s_waitcnt lgkmcnt(0)
	s_barrier
	ds_read2st64_b32 v[68:69], v49 offset0:76 offset1:78
	ds_read2st64_b32 v[128:129], v49 offset0:80 offset1:82
	v_mul_f32_e32 v76, v55, v70
	v_mul_f32_e32 v72, v55, v72
	s_waitcnt lgkmcnt(1)
	v_add_f32_e32 v46, 0, v68
	v_cndmask_b32_e64 v68, 0, v46, s[46:47]
	v_add_f32_e32 v46, v46, v69
	v_cndmask_b32_e64 v69, 0, v69, s[44:45]
	v_add_f32_e32 v70, v68, v69
	s_waitcnt lgkmcnt(0)
	v_add_f32_e32 v46, v46, v128
	v_cndmask_b32_e64 v68, 0, v128, s[42:43]
	v_add_f32_e32 v68, v70, v68
	v_cndmask_b32_e64 v70, 0, v129, s[40:41]
	v_add_f32_e32 v71, v68, v70
	v_add_f32_e32 v68, v73, v71
	v_mov_b32_e32 v70, v129
	v_pk_add_f32 v[46:47], v[46:47], v[70:71]
	v_sub_f32_e32 v68, v46, v68
	v_exp_f32_e32 v68, v68
	v_add_f32_e32 v69, v75, v71
	v_mul_f32_e32 v68, v72, v68
	v_sub_f32_e32 v69, v46, v69
	v_exp_f32_e32 v69, v69
	v_sub_f32_e32 v47, v46, v47
	v_add_f32_e32 v67, v81, v71
	v_sub_f32_e32 v67, v46, v67
	v_exp_f32_e32 v47, v47
	v_exp_f32_e32 v67, v67
	v_mul_f32_e32 v69, v76, v69
	v_mul_f32_e32 v47, v78, v47
	v_mul_f32_e32 v67, v79, v67
	v_cvt_pk_bf16_f32 v68, v68, v69
	v_cvt_pk_bf16_f32 v69, v47, v67
	ds_write_b64 v52, v[68:69] offset:8704
	s_and_saveexec_b64 s[4:5], s[38:39]
	s_cbranch_execz .LBB0_229
	v_exp_f32_e32 v47, v46
	ds_write_b32 v49, v47 offset:18944

; template <bool FULL>
; __device__ __forceinline__ void hgrn_item(LAS unsigned char* lds, const bf16_t* P, bf16_t* AB, int L, int hd, const float* lbv, const float* anorm, const float* S0, const float* Dd, int ns, float* Sout, float* Dout) {
;     ...
;         __syncthreads();
;         f32x4 acco = (f32x4){0.f, 0.f, 0.f, 0.f};
;         {
;             const u32x2 vv = *(const LAS u32x2*)(VsT + (16 * w + c16) * 20 + 4 * q4);
;             const bf16x4 vf = __builtin_bit_cast(bf16x4, vv);
;             if (FULL) {
;             bf16x8 qf[4], kf[4];
; #pragma unroll
;             for (int kq = 0; kq < 4; ++kq) {
;                 const u32x2 a0 = *(const LAS u32x2*)(Qt + c16 * 136 + 32 * kq + 4 * q4), a1 = *(const LAS u32x2*)(Qt + c16 * 136 + 32 * kq + 16 + 4 * q4);
;                 const u32x2 b0 = *(const LAS u32x2*)(Kt + c16 * 136 + 32 * kq + 4 * q4), b1 = *(const LAS u32x2*)(Kt + c16 * 136 + 32 * kq + 16 + 4 * q4);
;                 u32x4 qa = (u32x4){a0.x, a0.y, a1.x, a1.y}, ka = (u32x4){b0.x, b0.y, b1.x, b1.y};
;                 qf[kq] = __builtin_bit_cast(bf16x8, qa); kf[kq] = __builtin_bit_cast(bf16x8, ka);
;             }
;             f32x4 accA = (f32x4){0.f, 0.f, 0.f, 0.f};
; #pragma unroll
;             for (int kq = 0; kq < 4; ++kq) accA = __builtin_amdgcn_mfma_f32_16x16x32_bf16(kf[kq], qf[kq], accA, 0, 0, 0);
; #pragma unroll
;             for (int j = 0; j < 4; ++j) accA[j] = (c16 >= 4 * q4 + j) ? accA[j] : 0.f;
;             u32x2 pa; pa.x = cvt_pk_bf16(accA[0], accA[1]); pa.y = cvt_pk_bf16(accA[2], accA[3]);
;             const bf16x4 pA = __builtin_bit_cast(bf16x4, pa);
;             acco = __builtin_amdgcn_mfma_f32_16x16x16bf16_1k(pA, vf, (f32x4){0.f, 0.f, 0.f, 0.f}, 0, 0, 0);
; #pragma unroll
;             for (int kq = 0; kq < 4; ++kq) {
;                 u32x4 sp; sp.x = cvt_pk_bf16(accS[2 * kq][0], accS[2 * kq][1]); sp.y = cvt_pk_bf16(accS[2 * kq][2], accS[2 * kq][3]);
;                 sp.z = cvt_pk_bf16(accS[2 * kq + 1][0], accS[2 * kq + 1][1]); sp.w = cvt_pk_bf16(accS[2 * kq + 1][2], accS[2 * kq + 1][3]);
;                 acco = __builtin_amdgcn_mfma_f32_16x16x32_bf16(qf[kq], __builtin_bit_cast(bf16x8, sp), acco, 0, 0, 0);
;             }
;             }
; #pragma unroll
;             for (int mt = 0; mt < 8; ++mt) {
;                 const u32x2 kh2 = *(const LAS u32x2*)(KhT + (16 * mt + c16) * 20 + 4 * q4);
.LBB0_231:
	s_or_b64 exec, exec, s[4:5]
	v_add_u32_e32 v38, v57, v56
	s_waitcnt lgkmcnt(0)
	s_barrier
	ds_read_b64 v[36:37], v50 offset:13824
	ds_read_b128 v[156:159], v38 offset:18944
	v_add_f32_e32 v48, v48, v46
	v_add_u32_e32 v46, 0x2000, v58
	ds_read2_b64 v[68:71], v46 offset0:64 offset1:144
	v_add_u32_e32 v39, 0x2400, v58
	v_add_u32_e32 v47, 0x2800, v58
	v_add_u32_e32 v67, 0x3000, v58
	ds_read_b128 v[160:163], v38 offset:19008
	ds_read_b128 v[164:167], v38 offset:19072
	ds_read_b128 v[168:171], v38 offset:19136
	ds_read2_b64 v[196:199], v39 offset0:96 offset1:176
	ds_read_b128 v[172:175], v38 offset:19200
	ds_read_b128 v[176:179], v38 offset:19264
	ds_read2_b64 v[200:203], v47 offset0:128 offset1:208
	ds_read_b128 v[180:183], v38 offset:19328
	ds_read_b128 v[184:187], v38 offset:19392
	ds_read2_b64 v[204:207], v67 offset0:32 offset1:112
	s_add_u32 s2, s2, 0x2c000
	s_addc_u32 s3, s3, 0
	s_cmp_eq_u32 s2, 0x554000
	s_waitcnt lgkmcnt(11)
	v_pk_mul_f32 v[28:29], v[28:29], v[156:157]
	v_pk_mul_f32 v[30:31], v[30:31], v[158:159]
	s_waitcnt lgkmcnt(9)
	v_pk_mul_f32 v[24:25], v[24:25], v[160:161]
	v_pk_mul_f32 v[26:27], v[26:27], v[162:163]
	v_mfma_f32_16x16x16_bf16 v[28:31], v[68:69], v[36:37], v[28:31]
	s_waitcnt lgkmcnt(6)
	v_mfma_f32_16x16x16_bf16 v[24:27], v[70:71], v[36:37], v[24:27]
	v_pk_mul_f32 v[20:21], v[20:21], v[164:165]
	v_pk_mul_f32 v[22:23], v[22:23], v[166:167]
	v_pk_mul_f32 v[16:17], v[16:17], v[168:169]
	v_pk_mul_f32 v[18:19], v[18:19], v[170:171]
	v_mfma_f32_16x16x16_bf16 v[20:23], v[196:197], v[36:37], v[20:23]
	s_waitcnt lgkmcnt(3)
	v_mfma_f32_16x16x16_bf16 v[16:19], v[198:199], v[36:37], v[16:19]
	v_pk_mul_f32 v[12:13], v[12:13], v[172:173]
	v_pk_mul_f32 v[14:15], v[14:15], v[174:175]
	v_pk_mul_f32 v[8:9], v[8:9], v[176:177]
	v_pk_mul_f32 v[10:11], v[10:11], v[178:179]
	v_mfma_f32_16x16x16_bf16 v[12:15], v[200:201], v[36:37], v[12:15]
	s_waitcnt lgkmcnt(0)
	v_mfma_f32_16x16x16_bf16 v[8:11], v[202:203], v[36:37], v[8:11]
	v_pk_mul_f32 v[4:5], v[4:5], v[180:181]
	v_pk_mul_f32 v[6:7], v[6:7], v[182:183]
	v_pk_mul_f32 v[0:1], v[0:1], v[184:185]
	v_pk_mul_f32 v[2:3], v[2:3], v[186:187]
	v_mfma_f32_16x16x16_bf16 v[4:7], v[204:205], v[36:37], v[4:7]
	s_nop 0
	v_mfma_f32_16x16x16_bf16 v[0:3], v[206:207], v[36:37], v[0:3]
	s_cbranch_scc1 .LBB0_233
	s_waitcnt vmcnt(0)
	v_mov_b64_e32 v[38:39], v[34:35]
	v_mov_b64_e32 v[36:37], v[32:33]
	s_branch .LBB0_225
